# attention step loop head aligned to a 64-byte boundary (v66 otherwise; later code shifts by 16 bytes)
# baseline (speedup 1.0000x reference)
; __device__ __forceinline__ void ph_attn(Frame& F) {
;     ...
;         { const v4u z = (v4u){0u, 0u, 0u, 0u}; pk0 = __builtin_bit_cast(bf16x8_t, z); pk1 = pk0; pk2_ = pk0; pk3 = pk0;
; #pragma unroll
;           for (int j = 0; j < 8; ++j) vf[j] = pk0; }
; #pragma unroll
;         for (int r = 0; r < 16; ++r) { o0[r] = 0.f; o1[r] = 0.f; pB0[r] = 0.f; pB1[r] = 0.f; }
;         float m_run = -1e30f, l_run = 0.f;
;     ...
;         asm volatile("s_waitcnt vmcnt(0)" ::: "memory");
;         __syncthreads();
;         AT_DMA(0, 0, 0, 0); AT_DMA(1, AT_KB, 1, AT_VB); AT_DMA(2, 2 * AT_KB, 0, 0); AT_DMA(3, 3 * AT_KB, 1, AT_VB);
;         asm volatile("s_waitcnt vmcnt(0)" ::: "memory");
;         __syncthreads();
.LBB0_998:
	v_mov_b32_e32 v16, v3
	v_mov_b32_e32 v17, v3
	v_mov_b32_e32 v2, v3
	v_mov_b32_e32 v4, v3
	v_mov_b32_e32 v5, v3
	v_mov_b32_e32 v6, v3
	v_mov_b32_e32 v7, v3
	v_mov_b32_e32 v8, v3
	v_mov_b32_e32 v9, v3
	v_mov_b32_e32 v10, v3
	v_mov_b32_e32 v11, v3
	v_mov_b32_e32 v12, v3
	v_mov_b32_e32 v13, v3
	v_mov_b32_e32 v14, v3
	v_mov_b32_e32 v15, v3
	v_mov_b64_e32 v[34:35], v[16:17]
	v_mov_b32_e32 v68, 0
	v_mov_b64_e32 v[32:33], v[14:15]
	v_mov_b64_e32 v[30:31], v[12:13]
	v_mov_b64_e32 v[28:29], v[10:11]
	v_mov_b64_e32 v[26:27], v[8:9]
	v_mov_b64_e32 v[24:25], v[6:7]
	v_mov_b64_e32 v[22:23], v[4:5]
	v_mov_b64_e32 v[20:21], v[2:3]
	v_mov_b64_e32 v[18:19], v[16:17]
	s_add_i32 s37, s36, -1
	s_mov_b32 s38, 0
	s_movk_i32 s40, 0x4800
	s_movk_i32 s39, 0x2400
	s_mov_b32 s41, 0x9c00
	s_movk_i32 s15, 0x6800
	s_movk_i32 s14, 0x3400
	v_mov_b32_e32 v210, 0
	s_mov_b32 s56, 0xf149f2ca
	v_mov_b32_e32 v246, 0x3f80
	v_mov_b32_e32 v247, 0
	v_mov_b32_e32 v248, 0
	v_mov_b32_e32 v249, 0
	v_mov_b32_e32 v250, 0
	v_mov_b32_e32 v251, 0
	v_mov_b32_e32 v252, 0
	v_mov_b32_e32 v253, 0
	v_cndmask_b32_e64 v246, 0, v246, s[2:3]
	v_mov_b32_e32 v209, 0
	v_mov_b64_e32 v[16:17], v[14:15]
	v_mov_b64_e32 v[14:15], v[12:13]
	v_mov_b64_e32 v[12:13], v[10:11]
	v_mov_b64_e32 v[10:11], v[8:9]
	v_mov_b64_e32 v[8:9], v[6:7]
	v_mov_b64_e32 v[6:7], v[4:5]
	v_mov_b64_e32 v[4:5], v[2:3]
	s_mov_b32 s44, 0
	s_mov_b32 s46, 0
	v_mov_b32_e32 v69, v68
	v_mov_b32_e32 v70, v68
	v_mov_b32_e32 v71, v68
	v_mov_b32_e32 v80, v68
	v_mov_b32_e32 v81, v68
	v_mov_b32_e32 v82, v68
	v_mov_b32_e32 v83, v68
	v_mov_b32_e32 v76, v68
	v_mov_b32_e32 v77, v68
	v_mov_b32_e32 v78, v68
	v_mov_b32_e32 v79, v68
	v_mov_b32_e32 v72, v68
	v_mov_b32_e32 v73, v68
	v_mov_b32_e32 v74, v68
	v_mov_b32_e32 v75, v68
	v_mov_b32_e32 v148, v68
	v_mov_b32_e32 v149, v68
	v_mov_b32_e32 v150, v68
	v_mov_b32_e32 v151, v68
	v_mov_b32_e32 v160, v68
	v_mov_b32_e32 v161, v68
	v_mov_b32_e32 v162, v68
	v_mov_b32_e32 v163, v68
	v_mov_b32_e32 v184, v68
	v_mov_b32_e32 v185, v68
	v_mov_b32_e32 v186, v68
	v_mov_b32_e32 v187, v68
	v_mov_b32_e32 v164, v68
	v_mov_b32_e32 v165, v68
	v_mov_b32_e32 v166, v68
	v_mov_b32_e32 v167, v68
	v_mov_b32_e32 v180, v68
	v_mov_b32_e32 v181, v68
	v_mov_b32_e32 v182, v68
	v_mov_b32_e32 v183, v68
	v_mov_b32_e32 v156, v68
	v_mov_b32_e32 v157, v68
	v_mov_b32_e32 v158, v68
	v_mov_b32_e32 v159, v68
	v_mov_b32_e32 v176, v68
	v_mov_b32_e32 v177, v68
	v_mov_b32_e32 v178, v68
	v_mov_b32_e32 v179, v68
	v_mov_b32_e32 v152, v68
	v_mov_b32_e32 v153, v68
	v_mov_b32_e32 v154, v68
	v_mov_b32_e32 v155, v68
	s_add_i32 s42, s46, 4
	s_min_u32 s43, s42, s37
	s_add_i32 s42, s46, 2
	s_min_u32 s45, s42, s37
	s_mulk_i32 s43, 0x3000
	s_add_u32 s48, s10, s43
	s_addc_u32 s49, s11, 0
	s_lshl_b32 s43, s45, 13
	s_add_u32 s50, s12, s43
	s_addc_u32 s51, s13, 0
	s_add_i32 m0, s22, s38
	s_and_b64 s[52:53], s[4:5], exec
	.p2align	6
